# FFN-up sample-row GEMM items: next item 16 fragment loads prefetched during the current item (2 register sets)
# speedup vs baseline: 1.0260x; 1.0031x over previous
; #define LAS __attribute__((address_space(3)))
; __device__ __forceinline__ int hw_lane() { int ln; asm volatile("v_mbcnt_lo_u32_b32 %0, -1, 0\n\tv_mbcnt_hi_u32_b32 %0, -1, %0" : "=v"(ln)); return ln; }
; __device__ __forceinline__ int up_colmap(int n) {
;     return ((n & 128) ? DFF : 0) + (n >> 8) * 128 + (n & 127); }
; template <int NST, class Epi>
; __device__ __forceinline__ void gemm_small(const Ctx& c, const bf16* A, const bf16* Bt, int K, int nitems  , const Epi& E) {
;     LAS float* red = (LAS float*)c.lds; const int lane = hw_lane()  , wid = c.wave, r32 = lane & 31, hi = lane >> 5;
;     constexpr int CH = NST > 11 ? 11 : NST, KW = NST * 16;
;     static_assert(NST % CH == 0, "gemm_small K split");
;     if (c.bid < c.G / 2) return;
;     for (int it = c.G - 1 - c.bid; it < nitems; it += c.G - c.G / 2) {
;         const int rb = it & 3, n0 = (it >> 2) * 32;
;         f32x16s acc;
; #pragma unroll
;         for (int r = 0; r < 16; ++r) acc[r] = 0.f;
;         const bf16* ap = A + (size_t)(rb * 32 + r32) * K + wid * KW + 8 * hi; const bf16* bp = Bt + (size_t)(n0 + r32) * K + wid * KW + 8 * hi;
; #pragma unroll
;         for (int k0 = 0; k0 < NST; k0 += CH) {
;             bf16x8s af[CH], bf[CH];
; #pragma unroll
;             for (int u = 0; u < CH; ++u) { af[u] = *(const bf16x8s*)(ap + (k0 + u) * 16); bf[u] = *(const bf16x8s*)(bp + (k0 + u) * 16); }
; #pragma unroll
;             for (int u = 0; u < CH; ++u) acc = __builtin_amdgcn_mfma_f32_32x32x16_bf16(af[u], bf[u], acc, 0, 0, 0);
;         }
.LBB0_1883:
	s_and_b32 s28, s24, 0xffffffe0
	s_and_b32 s29, s25, 0x60
	v_or_b32_e32 v170, s29, v22
	v_or_b32_e32 v172, s28, v22
	v_lshlrev_b32_e32 v170, 11, v170
	v_ashrrev_i32_e32 v173, 31, v172
	v_mov_b32_e32 v171, 0
	v_lshl_add_u64 v[174:175], v[18:19], 0, v[170:171]
	v_lshlrev_b64 v[172:173], 11, v[172:173]
	v_lshl_add_u64 v[176:177], v[20:21], 0, v[172:173]
	global_load_dwordx4 v[26:29], v[174:175], off
	global_load_dwordx4 v[30:33], v[174:175], off offset:32
	global_load_dwordx4 v[34:37], v[174:175], off offset:64
	global_load_dwordx4 v[38:41], v[174:175], off offset:96
	global_load_dwordx4 v[42:45], v[174:175], off offset:128
	global_load_dwordx4 v[46:49], v[174:175], off offset:160
	global_load_dwordx4 v[50:53], v[174:175], off offset:192
	global_load_dwordx4 v[54:57], v[174:175], off offset:224
	global_load_dwordx4 v[58:61], v[176:177], off
	global_load_dwordx4 v[62:65], v[176:177], off offset:32
	global_load_dwordx4 v[66:69], v[176:177], off offset:64
	global_load_dwordx4 v[70:73], v[176:177], off offset:96
	global_load_dwordx4 v[74:77], v[176:177], off offset:128
	global_load_dwordx4 v[78:81], v[176:177], off offset:160
	global_load_dwordx4 v[82:85], v[176:177], off offset:192
	global_load_dwordx4 v[86:89], v[176:177], off offset:224
.Lgsu_A:
	s_and_b32 s28, s24, 0xffffffe0
	s_and_b32 s29, s25, 0x60
	s_bfe_i32 s30, s27, 0x10004
	s_and_b32 s33, s26, 0xffffff80
	v_add_u32_e32 v160, s9, v23
	v_add_u32_e32 v161, s12, v23
	v_add_u32_e32 v162, s16, v23
	v_add_u32_e32 v163, s29, v24
	s_and_b32 s29, s30, 0xb00
	v_mov_b32_e32 v164, 0x7f
	v_bitop3_b32 v164, s28, v164, v22 bitop3:0xc8
	s_add_i32 s29, s29, s33
	v_or_b32_e32 v166, s29, v164
	v_ashrrev_i32_e32 v167, 31, v166
	v_or_b32_e32 v168, s13, v163
	v_lshl_add_u64 v[166:167], v[166:167], 1, s[10:11]
	v_or_b32_e32 v163, s17, v163
	v_mad_i64_i32 v[168:169], s[28:29], v168, s41, v[166:167]
	v_mad_i64_i32 v[166:167], s[28:29], v163, s41, v[166:167]
	s_add_i32 s27, s27, s36
	s_add_i32 s26, s26, s40
	s_add_i32 s25, s25, s39
	s_add_i32 s24, s24, s38
	s_cmpk_lt_i32 s27, 0x2c0
	s_cbranch_scc0 .Lgsu_A_nopf
	s_and_b32 s28, s24, 0xffffffe0
	s_and_b32 s29, s25, 0x60
	v_or_b32_e32 v170, s29, v22
	v_or_b32_e32 v172, s28, v22
	v_lshlrev_b32_e32 v170, 11, v170
	v_ashrrev_i32_e32 v173, 31, v172
	v_mov_b32_e32 v171, 0
	v_lshl_add_u64 v[174:175], v[18:19], 0, v[170:171]
	v_lshlrev_b64 v[172:173], 11, v[172:173]
	v_lshl_add_u64 v[176:177], v[20:21], 0, v[172:173]
	global_load_dwordx4 v[90:93], v[174:175], off
	global_load_dwordx4 v[94:97], v[174:175], off offset:32
	global_load_dwordx4 v[98:101], v[174:175], off offset:64
	global_load_dwordx4 v[102:105], v[174:175], off offset:96
	global_load_dwordx4 v[106:109], v[174:175], off offset:128
	global_load_dwordx4 v[110:113], v[174:175], off offset:160
	global_load_dwordx4 v[114:117], v[174:175], off offset:192
	global_load_dwordx4 v[118:121], v[174:175], off offset:224
	global_load_dwordx4 v[122:125], v[176:177], off
	global_load_dwordx4 v[126:129], v[176:177], off offset:32
	global_load_dwordx4 v[130:133], v[176:177], off offset:64
	global_load_dwordx4 v[134:137], v[176:177], off offset:96
	global_load_dwordx4 v[138:141], v[176:177], off offset:128
	global_load_dwordx4 v[142:145], v[176:177], off offset:160
	global_load_dwordx4 v[146:149], v[176:177], off offset:192
	global_load_dwordx4 v[150:153], v[176:177], off offset:224
	s_waitcnt vmcnt(16)
	s_branch .Lgsu_A_mm

; template <int NST, class Epi>
; __device__ __forceinline__ void gemm_small(const Ctx& c, const bf16* A, const bf16* Bt, int K, int nitems  , const Epi& E) {
;     ...
;         for (int k0 = 0; k0 < NST; k0 += CH) {
;             bf16x8s af[CH], bf[CH];
; #pragma unroll
;             for (int u = 0; u < CH; ++u) { af[u] = *(const bf16x8s*)(ap + (k0 + u) * 16); bf[u] = *(const bf16x8s*)(bp + (k0 + u) * 16); }
; #pragma unroll
;             for (int u = 0; u < CH; ++u) acc = __builtin_amdgcn_mfma_f32_32x32x16_bf16(af[u], bf[u], acc, 0, 0, 0);
;         }
;         __syncthreads();
; #pragma unroll
;         for (int r = 0; r < 16; ++r) red[(size_t)(wid * 16 + r) * 64 + lane] = acc[r];
;         __syncthreads();
; #pragma unroll
;         for (int q = 0; q < 2; ++q) { const int r = wid * 2 + q; float v = 0.f;
; #pragma unroll
;             for (int w = 0; w < 8; ++w) v += red[(size_t)(w * 16 + r) * 64 + lane];
;             E(rb * 32 + (r & 3) + 8 * (r >> 2) + 4 * hi, n0 + r32, v); }
.Lgsu_A_mm:
	v_mfma_f32_32x32x16_bf16 v[2:17], v[26:29], v[58:61], 0
	v_mfma_f32_32x32x16_bf16 v[2:17], v[30:33], v[62:65], v[2:17]
	v_mfma_f32_32x32x16_bf16 v[2:17], v[34:37], v[66:69], v[2:17]
	v_mfma_f32_32x32x16_bf16 v[2:17], v[38:41], v[70:73], v[2:17]
	v_mfma_f32_32x32x16_bf16 v[2:17], v[42:45], v[74:77], v[2:17]
	v_mfma_f32_32x32x16_bf16 v[2:17], v[46:49], v[78:81], v[2:17]
	v_mfma_f32_32x32x16_bf16 v[2:17], v[50:53], v[82:85], v[2:17]
	v_mfma_f32_32x32x16_bf16 v[2:17], v[54:57], v[86:89], v[2:17]
	s_barrier
	s_nop 11
	ds_write2st64_b32 v160, v2, v3 offset0:4 offset1:5
	ds_write2st64_b32 v160, v4, v5 offset0:6 offset1:7
	ds_write2st64_b32 v160, v6, v7 offset0:8 offset1:9
	ds_write2st64_b32 v160, v8, v9 offset0:10 offset1:11
	ds_write2st64_b32 v160, v10, v11 offset0:12 offset1:13
	ds_write2st64_b32 v160, v12, v13 offset0:14 offset1:15
	ds_write2st64_b32 v160, v14, v15 offset0:16 offset1:17
	ds_write2st64_b32 v160, v16, v17 offset0:18 offset1:19
	s_waitcnt lgkmcnt(0)
	s_barrier
	ds_read2st64_b32 v[180:181], v161 offset0:4 offset1:20
	ds_read2st64_b32 v[182:183], v161 offset0:36 offset1:52
	ds_read2st64_b32 v[184:185], v161 offset0:68 offset1:84
	ds_read2st64_b32 v[186:187], v161 offset0:100 offset1:116
	ds_read2st64_b32 v[188:189], v162 offset0:4 offset1:20
	ds_read2st64_b32 v[190:191], v162 offset0:36 offset1:52
	ds_read2st64_b32 v[192:193], v162 offset0:68 offset1:84
	ds_read2st64_b32 v[194:195], v162 offset0:100 offset1:116
	s_waitcnt lgkmcnt(0)
	v_add_f32_e32 v196, 0, v180
	v_add_f32_e32 v197, 0, v188
	v_add_f32_e32 v196, v196, v181
	v_add_f32_e32 v197, v197, v189
	v_add_f32_e32 v196, v196, v182
	v_add_f32_e32 v197, v197, v190
	v_add_f32_e32 v196, v196, v183
	v_add_f32_e32 v197, v197, v191
	v_add_f32_e32 v196, v196, v184
	v_add_f32_e32 v197, v197, v192
	v_add_f32_e32 v196, v196, v185
	v_add_f32_e32 v197, v197, v193
	v_add_f32_e32 v196, v196, v186
	v_add_f32_e32 v197, v197, v194
	v_add_f32_e32 v196, v196, v187
	v_add_f32_e32 v197, v197, v195
	v_bfe_u32 v198, v196, 16, 1
	v_bfe_u32 v199, v197, 16, 1
	v_add3_u32 v196, v196, v198, s15
	v_add3_u32 v197, v197, v199, s15
	global_store_short_d16_hi v[168:169], v196, off
	global_store_short_d16_hi v[166:167], v197, off
	s_barrier
	s_cmpk_lt_i32 s27, 0x2c0
	s_cbranch_scc1 .Lgsu_B
	s_branch .Lgsu_exit
.Lgsu_B:
	s_and_b32 s28, s24, 0xffffffe0
	s_and_b32 s29, s25, 0x60
	s_bfe_i32 s30, s27, 0x10004
	s_and_b32 s33, s26, 0xffffff80
	v_add_u32_e32 v160, s9, v23
	v_add_u32_e32 v161, s12, v23
	v_add_u32_e32 v162, s16, v23
	v_add_u32_e32 v163, s29, v24
	s_and_b32 s29, s30, 0xb00
	v_mov_b32_e32 v164, 0x7f
	v_bitop3_b32 v164, s28, v164, v22 bitop3:0xc8
	s_add_i32 s29, s29, s33
	v_or_b32_e32 v166, s29, v164
	v_ashrrev_i32_e32 v167, 31, v166
	v_or_b32_e32 v168, s13, v163
	v_lshl_add_u64 v[166:167], v[166:167], 1, s[10:11]
	v_or_b32_e32 v163, s17, v163
	v_mad_i64_i32 v[168:169], s[28:29], v168, s41, v[166:167]
	v_mad_i64_i32 v[166:167], s[28:29], v163, s41, v[166:167]
	s_add_i32 s27, s27, s36
	s_add_i32 s26, s26, s40
	s_add_i32 s25, s25, s39
	s_add_i32 s24, s24, s38
	s_cmpk_lt_i32 s27, 0x2c0
	s_cbranch_scc0 .Lgsu_B_nopf
	s_and_b32 s28, s24, 0xffffffe0
	s_and_b32 s29, s25, 0x60
	v_or_b32_e32 v170, s29, v22
	v_or_b32_e32 v172, s28, v22
	v_lshlrev_b32_e32 v170, 11, v170
	v_ashrrev_i32_e32 v173, 31, v172
	v_mov_b32_e32 v171, 0
	v_lshl_add_u64 v[174:175], v[18:19], 0, v[170:171]
	v_lshlrev_b64 v[172:173], 11, v[172:173]
	v_lshl_add_u64 v[176:177], v[20:21], 0, v[172:173]
	global_load_dwordx4 v[26:29], v[174:175], off
	global_load_dwordx4 v[30:33], v[174:175], off offset:32
	global_load_dwordx4 v[34:37], v[174:175], off offset:64
	global_load_dwordx4 v[38:41], v[174:175], off offset:96
	global_load_dwordx4 v[42:45], v[174:175], off offset:128
	global_load_dwordx4 v[46:49], v[174:175], off offset:160
	global_load_dwordx4 v[50:53], v[174:175], off offset:192
	global_load_dwordx4 v[54:57], v[174:175], off offset:224
	global_load_dwordx4 v[58:61], v[176:177], off
	global_load_dwordx4 v[62:65], v[176:177], off offset:32
	global_load_dwordx4 v[66:69], v[176:177], off offset:64
	global_load_dwordx4 v[70:73], v[176:177], off offset:96
	global_load_dwordx4 v[74:77], v[176:177], off offset:128
	global_load_dwordx4 v[78:81], v[176:177], off offset:160
	global_load_dwordx4 v[82:85], v[176:177], off offset:192
	global_load_dwordx4 v[86:89], v[176:177], off offset:224
	s_waitcnt vmcnt(16)
	s_branch .Lgsu_B_mm

; template <int NST, class Epi>
; __device__ __forceinline__ void gemm_small(const Ctx& c, const bf16* A, const bf16* Bt, int K, int nitems  , const Epi& E) {
;     ...
;             for (int u = 0; u < CH; ++u) acc = __builtin_amdgcn_mfma_f32_32x32x16_bf16(af[u], bf[u], acc, 0, 0, 0);
;         }
;         __syncthreads();
; #pragma unroll
;         for (int r = 0; r < 16; ++r) red[(size_t)(wid * 16 + r) * 64 + lane] = acc[r];
;         __syncthreads();
; #pragma unroll
;         for (int q = 0; q < 2; ++q) { const int r = wid * 2 + q; float v = 0.f;
; #pragma unroll
;             for (int w = 0; w < 8; ++w) v += red[(size_t)(w * 16 + r) * 64 + lane];
;             E(rb * 32 + (r & 3) + 8 * (r >> 2) + 4 * hi, n0 + r32, v); }
;         __syncthreads();
.Lgsu_B_mm:
	v_mfma_f32_32x32x16_bf16 v[2:17], v[90:93], v[122:125], 0
	v_mfma_f32_32x32x16_bf16 v[2:17], v[94:97], v[126:129], v[2:17]
	v_mfma_f32_32x32x16_bf16 v[2:17], v[98:101], v[130:133], v[2:17]
	v_mfma_f32_32x32x16_bf16 v[2:17], v[102:105], v[134:137], v[2:17]
	v_mfma_f32_32x32x16_bf16 v[2:17], v[106:109], v[138:141], v[2:17]
	v_mfma_f32_32x32x16_bf16 v[2:17], v[110:113], v[142:145], v[2:17]
	v_mfma_f32_32x32x16_bf16 v[2:17], v[114:117], v[146:149], v[2:17]
	v_mfma_f32_32x32x16_bf16 v[2:17], v[118:121], v[150:153], v[2:17]
	s_barrier
	s_nop 11
	ds_write2st64_b32 v160, v2, v3 offset0:4 offset1:5
	ds_write2st64_b32 v160, v4, v5 offset0:6 offset1:7
	ds_write2st64_b32 v160, v6, v7 offset0:8 offset1:9
	ds_write2st64_b32 v160, v8, v9 offset0:10 offset1:11
	ds_write2st64_b32 v160, v10, v11 offset0:12 offset1:13
	ds_write2st64_b32 v160, v12, v13 offset0:14 offset1:15
	ds_write2st64_b32 v160, v14, v15 offset0:16 offset1:17
	ds_write2st64_b32 v160, v16, v17 offset0:18 offset1:19
	s_waitcnt lgkmcnt(0)
	s_barrier
	ds_read2st64_b32 v[180:181], v161 offset0:4 offset1:20
	ds_read2st64_b32 v[182:183], v161 offset0:36 offset1:52
	ds_read2st64_b32 v[184:185], v161 offset0:68 offset1:84
	ds_read2st64_b32 v[186:187], v161 offset0:100 offset1:116
	ds_read2st64_b32 v[188:189], v162 offset0:4 offset1:20
	ds_read2st64_b32 v[190:191], v162 offset0:36 offset1:52
	ds_read2st64_b32 v[192:193], v162 offset0:68 offset1:84
	ds_read2st64_b32 v[194:195], v162 offset0:100 offset1:116
	s_waitcnt lgkmcnt(0)
	v_add_f32_e32 v196, 0, v180
	v_add_f32_e32 v197, 0, v188
	v_add_f32_e32 v196, v196, v181
	v_add_f32_e32 v197, v197, v189
	v_add_f32_e32 v196, v196, v182
	v_add_f32_e32 v197, v197, v190
	v_add_f32_e32 v196, v196, v183
	v_add_f32_e32 v197, v197, v191
	v_add_f32_e32 v196, v196, v184
	v_add_f32_e32 v197, v197, v192
	v_add_f32_e32 v196, v196, v185
	v_add_f32_e32 v197, v197, v193
	v_add_f32_e32 v196, v196, v186
	v_add_f32_e32 v197, v197, v194
	v_add_f32_e32 v196, v196, v187
	v_add_f32_e32 v197, v197, v195
	v_bfe_u32 v198, v196, 16, 1
	v_bfe_u32 v199, v197, 16, 1
	v_add3_u32 v196, v196, v198, s15
	v_add3_u32 v197, v197, v199, s15
	global_store_short_d16_hi v[168:169], v196, off
	global_store_short_d16_hi v[166:167], v197, off
	s_barrier
	s_cmpk_lt_i32 s27, 0x2c0
	s_cbranch_scc1 .Lgsu_A
	s_branch .Lgsu_exit
.Lgsu_exit:
	s_movk_i32 s33, 0x4000
	s_branch .LBB0_1880
